# rawA row pitch 3360 -> 3376 elements (6752 B, odd multiple of 32 B) on top of v38
# speedup vs baseline: 1.0047x; 1.0047x over previous
; #define LAS __attribute__((address_space(3)))
; __device__ __forceinline__ unsigned xb_ld(unsigned* p)              { return __hip_atomic_load(p, __ATOMIC_RELAXED, __HIP_MEMORY_SCOPE_AGENT); }
; __device__ __forceinline__ unsigned xb_add(unsigned* p, unsigned v) { return __hip_atomic_fetch_add(p, v, __ATOMIC_RELAXED, __HIP_MEMORY_SCOPE_AGENT); }
; __device__ __forceinline__ unsigned xb_xcc_id() { return (unsigned)__builtin_amdgcn_s_getreg((3 << 11) | 20) & 0xFu; }
;     __host__ __device__ bool next(int i, Unit& u) const {
;         const long L = (long)i * G + c; if (L >= nwg) return false;
;         int wgid = (int)L; { const int q = nwg / NXCD, r = nwg % NXCD, xcd = wgid % NXCD, off = wgid / NXCD; wgid = (xcd < r ? xcd * (q + 1) : r * (q + 1) + (xcd - r) * q) + off; }
;         const int nig = WGM * nN, gid = wgid / nig, fm = gid * WGM, gsz = (nM - fm) < WGM ? (nM - fm) : WGM;
;         u.pm = fm + ((wgid % nig) % gsz); u.pn = (wgid % nig) / gsz; return true;
; __device__ __forceinline__ XcdBarrier xcd_barrier_post(unsigned* bar, volatile LAS unsigned* st) {
;     XcdBarrier b; b.bar = bar; b.x = xb_xcc_id(); b.st = st;
;     if (threadIdx.x == 0) (void)xb_add(&bar[XB_XCNT(b.x)], 1u);
;     return b;
; }
; __device__ __forceinline__ void xcd_barrier_complete(unsigned* bar, unsigned x, unsigned& nloc, unsigned& nx) {
;     const unsigned G = gridDim.x * gridDim.y * gridDim.z;
;     unsigned sum, cnt, mine, sp = 0u;
;     for (;;) {
;         sum = 0u; cnt = 0u; mine = 0u;
; #pragma unroll
;         for (unsigned j = 0; j < 16; ++j) { const unsigned c = xb_ld(&bar[XB_XCNT(j)]); sum += c; cnt += (c > 0u) ? 1u : 0u; mine = (j == x) ? c : mine; }
;         if (sum == G) break;
;         __builtin_amdgcn_s_sleep(1);
;         if ((++sp & 255u) == 0u) { if (xb_ld(&bar[XB_TMO])) break; if (sp > XB_SPIN_CAP) { atomicAdd(&bar[XB_TMO], 1u); break; } }
;     }
;     nloc = mine > 0u ? mine : 1u; nx = cnt > 0u ? cnt : 1u;
; }
.LBB0_60:
	v_writelane_b32 v254, s14, 40
	s_nop 1
	v_writelane_b32 v254, s15, 41
	s_or_b64 exec, exec, s[4:5]
	s_ashr_i32 s33, s2, 31
	s_lshr_b32 s4, s33, 29
	s_add_i32 s4, s2, s4
	s_and_b32 s5, s4, -8
	s_sub_i32 s5, s2, s5
	s_lshl_b32 s6, s5, 6
	s_cmp_lt_i32 s5, 0
	s_mul_i32 s7, s5, 0x41
	s_cselect_b32 s10, s7, s6
	s_lshl_b32 s6, s5, 8
	s_cmp_lt_i32 s5, 0
	s_mul_i32 s7, s5, 0x101
	s_cselect_b32 s11, s7, s6
	s_lshl_b32 s6, s5, 7
	s_cmp_lt_i32 s5, 0
	s_movk_i32 s7, 0xe1
	s_mul_i32 s8, s5, 0x81
	s_cselect_b32 s7, s7, 0xe0
	s_cselect_b32 s13, s8, s6
	s_lshl_b32 s8, s12, 14
	s_lshl_b32 s73, s58, 3
	s_mul_i32 s6, s59, s58
	s_add_i32 s8, s8, 0
	s_mul_i32 s6, s6, s27
	v_writelane_b32 v255, s8, 0
	s_add_u32 s8, s64, 0x200
	v_writelane_b32 v255, s6, 1
	s_addc_u32 s9, s65, 0
	v_writelane_b32 v255, s8, 2
	s_mul_i32 s5, s7, s5
	s_mov_b32 s97, 0
	v_writelane_b32 v255, s9, 3
	s_add_u32 s8, s64, 0x1000
	s_addc_u32 s9, s65, 0
	v_writelane_b32 v255, s8, 4
	v_and_b32_e32 v2, 0xff, v0
	v_mov_b32_e32 v3, 0
	v_writelane_b32 v255, s9, 5
	s_add_u32 s8, s64, 0x1100
	s_addc_u32 s9, s65, 0
	s_add_u32 s74, s64, 0x1200
	s_addc_u32 s75, s65, 0
	s_add_u32 s76, s64, 0x1300
	s_addc_u32 s77, s65, 0
	v_writelane_b32 v255, s8, 6
	s_cmp_eq_u32 s26, 15
	v_lshlrev_b32_e32 v166, 2, v2
	v_writelane_b32 v255, s9, 7
	s_cselect_b64 s[8:9], -1, 0
	v_writelane_b32 v255, s8, 8
	s_cmp_eq_u32 s26, 14
	v_mbcnt_lo_u32_b32 v2, -1, 0
	v_writelane_b32 v255, s9, 9
	s_cselect_b64 s[8:9], -1, 0
	v_writelane_b32 v255, s8, 10
	s_cmp_eq_u32 s26, 13
	v_add_u32_e32 v1, 0x24800, v1
	v_writelane_b32 v255, s9, 11
	s_cselect_b64 s[8:9], -1, 0
	v_writelane_b32 v255, s8, 12
	s_cmp_eq_u32 s26, 12
	v_mov_b32_e32 v165, 0x358637bd
	v_writelane_b32 v255, s9, 13
	s_cselect_b64 s[8:9], -1, 0
	v_writelane_b32 v255, s8, 14
	s_cmp_eq_u32 s26, 11
	v_mov_b32_e32 v199, 1
	v_writelane_b32 v255, s9, 15
	s_cselect_b64 s[8:9], -1, 0
	v_writelane_b32 v255, s8, 16
	s_cmp_eq_u32 s26, 10
	v_mov_b32_e32 v200, 0x3a27c5ac
	v_writelane_b32 v255, s9, 17
	s_cselect_b64 s[8:9], -1, 0
	v_writelane_b32 v255, s8, 18
	s_cmp_eq_u32 s26, 9
	v_mov_b32_e32 v201, 0x3eaaaaab
	v_writelane_b32 v255, s9, 19
	s_cselect_b64 s[8:9], -1, 0
	v_writelane_b32 v255, s8, 20
	s_cmp_eq_u32 s26, 8
	s_mov_b32 s63, 0x27000
	v_writelane_b32 v255, s9, 21
	s_cselect_b64 s[8:9], -1, 0
	v_writelane_b32 v255, s8, 22
	s_cmp_eq_u32 s26, 7
	s_brev_b32 s62, -2
	v_writelane_b32 v255, s9, 23
	s_cselect_b64 s[8:9], -1, 0
	v_writelane_b32 v255, s8, 24
	s_cmp_eq_u32 s26, 6
	v_mbcnt_hi_u32_b32 v198, -1, v2
	v_writelane_b32 v255, s9, 25
	s_cselect_b64 s[8:9], -1, 0
	v_writelane_b32 v255, s8, 26
	s_cmp_eq_u32 s26, 5
	v_mov_b32_e32 v220, v3
	v_writelane_b32 v255, s9, 27
	s_cselect_b64 s[8:9], -1, 0
	v_writelane_b32 v255, s8, 28
	s_cmp_eq_u32 s26, 4
	v_mov_b32_e32 v221, v3
	v_writelane_b32 v255, s9, 29
	s_cselect_b64 s[8:9], -1, 0
	v_writelane_b32 v255, s8, 30
	s_cmp_eq_u32 s26, 3
	v_mov_b32_e32 v222, v3
	v_writelane_b32 v255, s9, 31
	s_cselect_b64 s[8:9], -1, 0
	v_writelane_b32 v255, s8, 32
	s_cmp_eq_u32 s26, 2
	v_mov_b32_e32 v223, v3
	v_writelane_b32 v255, s9, 33
	s_cselect_b64 s[8:9], -1, 0
	v_writelane_b32 v255, s8, 34
	s_cmp_eq_u32 s26, 1
	v_mov_b32_e32 v202, 0x1a60
	v_writelane_b32 v255, s9, 35
	s_cselect_b64 s[8:9], -1, 0
	v_writelane_b32 v255, s8, 36
	s_cmp_eq_u32 s26, 0
	v_mov_b32_e32 v203, 0xffffe5a0
	v_writelane_b32 v255, s9, 37
	s_cselect_b64 s[8:9], -1, 0
	s_lshl_b32 s6, s26, 8
	v_writelane_b32 v255, s8, 38
	s_add_u32 s6, s64, s6
	v_mov_b32_e32 v169, 1.0
	v_writelane_b32 v255, s9, 39
	s_addc_u32 s8, s65, 0
	s_add_u32 s14, s6, 0x1400
	s_addc_u32 s15, s8, 0
	v_writelane_b32 v255, s14, 40
	v_mov_b32_e32 v204, 0xfffff2d0
	v_mov_b32_e32 v205, 0xd30
	v_writelane_b32 v255, s15, 41
	s_add_u32 s14, s6, 0x2400
	s_addc_u32 s15, s8, 0
	v_writelane_b32 v255, s14, 42
	s_add_u32 s8, s64, 0x3400
	s_addc_u32 s9, s65, 0
	v_writelane_b32 v255, s15, 43
	v_writelane_b32 v255, s8, 44
	v_mov_b32_e32 v206, 0x42800000
	v_not_b32_e32 v207, 63
	v_writelane_b32 v255, s9, 45
	s_add_u32 s8, s64, 0x3500
	s_addc_u32 s9, s65, 0
	v_writelane_b32 v255, s8, 46
	s_cmpk_lt_i32 s2, 0x700
	v_mov_b64_e32 v[172:173], 0x800
	v_writelane_b32 v255, s9, 47
	s_cselect_b64 s[8:9], -1, 0
	s_ashr_i32 s14, s4, 3
	s_add_i32 s5, s5, s14
	s_mul_hi_i32 s4, s5, 0x92492493
	s_add_i32 s4, s4, s5
	s_lshr_b32 s6, s4, 31
	s_ashr_i32 s4, s4, 6
	s_add_i32 s4, s4, s6
	s_mul_i32 s6, s4, 0x70
	s_sub_i32 s5, s5, s6
	s_bfe_i32 s6, s5, 0x80000
	s_bfe_u32 s6, s6, 0x3000c
	s_add_i32 s7, s5, s6
	s_bfe_i32 s6, s7, 0x80000
	s_and_b32 s7, s7, 0xf8
	v_writelane_b32 v255, s8, 48
	s_sub_i32 s5, s5, s7
	s_lshl_b32 s4, s4, 3
	v_writelane_b32 v255, s9, 49
	s_sext_i32_i16 s8, s6
	s_sext_i32_i8 s5, s5
	s_lshr_b32 s6, s8, 3
	s_add_i32 s26, s4, s5
	s_ashr_i32 s4, s8, 3
	s_ashr_i32 s59, s58, 31
	s_cmpk_lt_i32 s2, 0x100
	v_writelane_b32 v255, s4, 50
	s_cselect_b64 s[4:5], -1, 0
	v_writelane_b32 v255, s4, 51
	s_bfe_u32 s87, s3, 0x10006
	s_mul_i32 s21, s87, 0x4100
	v_writelane_b32 v255, s5, 52
	s_lshl_b32 s4, s12, 12
	s_and_b32 s4, s4, 0x3000
	s_add_i32 s4, s4, 0
	s_add_i32 s4, s4, 0x20800
	v_writelane_b32 v255, s4, 53
; #define LAS __attribute__((address_space(3)))
; #define KARG() ({ const CAS Params* kp_ = (const CAS Params*)__builtin_amdgcn_kernarg_segment_ptr(); asm volatile("" : "+s"(kp_)); kp_; })
; __device__ __forceinline__ void scan_phase(int l, LAS unsigned char* lds, int wave, int lane) {
;     asm volatile("" : "+v"(lane));
;     unsigned char* ws = KARG()->ws;
;     LAS float* ring = (LAS float*)(lds + 32768);
;     for (int bh = blockIdx.x; bh < BATCH * 16; bh += gridDim.x) {
;         const int b = bh >> 4, h = bh & 15;
;         LAS f32x4* sts = (LAS f32x4*)lds + (wave & 3) * 512 + lane;
;         LAS float* cst = (LAS float*)(lds + CST_OFF);
;         LAS float* ybw = (LAS float*)(lds + 133120) + (wave & 3) * 2 * CHS * 32;
;         const int dirw = wave & 1, rhw = (wave >> 1) & 1;
;         bf16* yb2 = (bf16*)(ws + OFF_YS) + (size_t)b * SEQ * DM + h * 64 + 32 * rhw + 2 * (lane & 15);
;         prep_consts(l, h, cst);
	s_lshl_b32 s4, s12, 10
	v_writelane_b32 v255, s4, 54
	s_bfe_u32 s4, s3, 0x10007
	s_lshl_b32 s7, s4, 5
	s_cmpk_gt_u32 s3, 0xff
	s_cselect_b64 s[92:93], -1, 0
	s_and_b32 s5, s3, 0xffffff80
	s_cmpk_lg_i32 s5, 0x100
	s_cselect_b64 s[94:95], -1, 0
	s_add_i32 s5, s21, 0
	s_cmp_eq_u32 s87, 0
	v_writelane_b32 v255, s5, 55
	s_cselect_b64 s[38:39], -1, 0
	s_lshl_b32 s5, s87, 8
	s_add_i32 s69, s5, 0
	s_lshl_b32 s8, s87, 6
	s_add_i32 s68, s69, 0x25800
	s_add_i32 s69, s69, 0x25600
	s_lshl_b32 s4, s4, 7
	s_lshl_b32 s5, s87, 17
	s_or_b32 s9, s8, 0x80
	s_lshl_b32 s15, s87, 21
	s_lshl_b32 s16, s87, 16
	s_lshl_b32 s17, s87, 4
	s_cmpk_lt_i32 s2, 0x400
	v_writelane_b32 v255, s15, 56
	s_cselect_b64 s[18:19], -1, 0
	v_writelane_b32 v255, s18, 57
	s_lshl_b32 s15, s12, 4
	s_cmpk_lt_i32 s2, 0x800
	v_writelane_b32 v255, s19, 58
	s_mulk_i32 s12, 0x1100
	v_writelane_b32 v255, s15, 59
	s_cselect_b64 s[18:19], -1, 0
	s_add_i32 s12, s12, 0
	v_writelane_b32 v255, s18, 60
	s_add_i32 s12, s12, 0x11800
	s_cmpk_lt_i32 s2, 0x200
	v_writelane_b32 v255, s19, 61
	v_writelane_b32 v255, s12, 62
	s_cselect_b64 s[18:19], -1, 0
	s_add_i32 s12, s13, s14
	s_ashr_i32 s13, s12, 31
	s_lshr_b32 s13, s13, 26
	s_add_i32 s13, s12, s13
	s_and_b32 s15, s13, 0xffc0
	s_sub_i32 s12, s12, s15
	s_bfe_i32 s15, s12, 0x80000
	s_bfe_u32 s15, s15, 0x3000c
	v_writelane_b32 v255, s18, 63
	s_add_i32 s15, s12, s15
	s_add_i32 s11, s11, s14
	v_writelane_b32 v254, s19, 0
	s_and_b32 s18, s15, 0xf8
	s_sub_i32 s12, s12, s18
	s_ashr_i32 s18, s11, 31
	s_lshr_b32 s18, s18, 25
	s_add_i32 s18, s11, s18
	s_and_b32 s19, s18, 0xff80
	s_sub_i32 s11, s11, s19
	s_bfe_i32 s19, s11, 0x80000
	s_bfe_u32 s19, s19, 0x3000c
	s_add_i32 s19, s11, s19
	s_and_b32 s20, s19, 0xf8
	s_add_i32 s10, s10, s14
	s_sub_i32 s20, s11, s20
	s_ashr_i32 s11, s10, 31
	s_lshr_b32 s11, s11, 27
	s_add_i32 s14, s10, s11
	s_and_b32 s11, s14, 0xffe0
	s_sub_i32 s10, s10, s11
	s_bfe_i32 s11, s10, 0x80000
	s_bfe_u32 s11, s11, 0x3000c
	s_add_i32 s22, s10, s11
	s_and_b32 s11, s22, 0xf8
	s_sub_i32 s23, s10, s11
	s_bfe_i64 s[10:11], s[6:7], 0x100000
	s_lshl_b64 s[10:11], s[10:11], 19
	v_writelane_b32 v254, s10, 1
	s_ashr_i32 s6, s13, 6
	s_lshl_b32 s6, s6, 3
	v_writelane_b32 v254, s11, 2
	s_bfe_i32 s10, s15, 0x80000
	s_sext_i32_i16 s10, s10
	s_sext_i32_i8 s11, s12
	s_add_i32 s12, s6, s11
	s_ashr_i32 s6, s10, 3
	v_writelane_b32 v254, s6, 3
	s_lshr_b32 s6, s10, 3
	s_bfe_i64 s[10:11], s[6:7], 0x100000
	s_lshl_b64 s[10:11], s[10:11], 19
	v_writelane_b32 v254, s10, 4
	s_ashr_i32 s6, s18, 7
	s_lshl_b32 s6, s6, 3
	v_writelane_b32 v254, s11, 5
	s_bfe_i32 s10, s19, 0x80000
	s_sext_i32_i16 s10, s10
	s_sext_i32_i8 s11, s20
	s_add_i32 s28, s6, s11
	s_ashr_i32 s6, s10, 3
	v_writelane_b32 v254, s6, 6
	s_lshr_b32 s6, s10, 3
	s_bfe_i64 s[10:11], s[6:7], 0x100000
	s_lshl_b64 s[10:11], s[10:11], 19
	v_writelane_b32 v254, s10, 7
	s_ashr_i32 s6, s14, 5
	s_lshl_b32 s6, s6, 3
	v_writelane_b32 v254, s11, 8
	s_bfe_i32 s10, s22, 0x80000
	s_sext_i32_i16 s10, s10
	s_sext_i32_i8 s11, s23
	s_add_i32 s14, s6, s11
	s_ashr_i32 s6, s10, 3
	v_writelane_b32 v254, s6, 9
	s_lshr_b32 s6, s10, 3
	s_bfe_i64 s[10:11], s[6:7], 0x100000
	s_lshl_b64 s[10:11], s[10:11], 19
	v_writelane_b32 v254, s10, 10
	s_lshl_b32 s3, s3, 6
	s_and_b32 s3, s3, 0x3000
	v_writelane_b32 v254, s11, 11
	v_writelane_b32 v254, s3, 12
	s_or_b32 s3, s21, s4
	s_add_i32 s3, s3, 0x8510
	v_writelane_b32 v254, s3, 13
	s_lshl_b32 s3, s2, 15
	s_or_b32 s3, s3, 0x7840
	v_writelane_b32 v254, s3, 14
	s_lshl_b32 s3, s7, 1
	v_writelane_b32 v254, s3, 15
	s_add_i32 s3, s21, 0x8610
	v_writelane_b32 v254, s3, 16
	s_add_i32 s3, s21, 0x8410
	v_writelane_b32 v254, s3, 17
	s_lshl_b32 s3, s2, 7
	v_writelane_b32 v254, s3, 18
	s_add_i32 s3, 0, 0x26004
	v_writelane_b32 v254, s3, 19
	s_mov_b32 s6, s26
	s_ashr_i32 s27, s26, 31
	v_writelane_b32 v254, s6, 20
	s_ashr_i32 s13, s12, 31
	s_ashr_i32 s29, s28, 31
	v_writelane_b32 v254, s7, 21
	s_lshl_b64 s[6:7], s[26:27], 19
	v_writelane_b32 v254, s6, 22
	s_ashr_i32 s15, s14, 31
	v_mov_b64_e32 v[174:175], 0x7ff
	v_writelane_b32 v254, s7, 23
	s_mov_b32 s6, s12
	v_writelane_b32 v254, s6, 24
	v_mov_b64_e32 v[176:177], 0x200
	v_mov_b64_e32 v[178:179], 0x1ff
	v_writelane_b32 v254, s7, 25
	s_lshl_b64 s[6:7], s[12:13], 19
	v_writelane_b32 v254, s6, 26
	s_mov_b32 s18, 0x9400
	s_mov_b32 s19, 0x800000
	v_writelane_b32 v254, s7, 27
	s_mov_b32 s6, s28
	v_writelane_b32 v254, s6, 28
	s_movk_i32 s22, 0x1a60
	s_movk_i32 s23, 0x37f
	v_writelane_b32 v254, s7, 29
	s_lshl_b64 s[6:7], s[28:29], 19
	v_writelane_b32 v254, s6, 30
	s_movk_i32 s24, 0x7ff
	s_movk_i32 s72, 0x410
	v_writelane_b32 v254, s7, 31
	s_mov_b32 s6, s14
	v_writelane_b32 v254, s6, 32
	s_movk_i32 s25, 0x1000
	s_mov_b64 s[10:11], 0x40000
	v_writelane_b32 v254, s7, 33
	s_lshl_b64 s[6:7], s[14:15], 19
	v_writelane_b32 v254, s6, 34
	s_mov_b64 s[12:13], 0x12100000
	s_mov_b64 s[14:15], 0x80
	v_writelane_b32 v254, s7, 35
	s_mov_b32 s6, s97
	v_writelane_b32 v254, s6, 36
	s_mov_b32 s3, 1.0
	s_mov_b32 s20, 0x3e800000
	v_writelane_b32 v254, s7, 37
	v_writelane_b32 v254, s56, 38
	s_mov_b32 s88, 0x3e000000
	s_brev_b32 s86, 60
	v_writelane_b32 v254, s57, 39
	s_branch .LBB0_63
